# code placement: the seven GEMM K-loop headers padded to 64-byte alignment (s_nop before the loop label), otherwise v44
# speedup vs baseline: 1.0116x; 1.0070x over previous
;     __device__ __forceinline__ bool next(int i, Unit& u) const { u.z = 0; return o.tile(i, u); }
;     __device__ __forceinline__ long a_off(const Unit& u) const { return (long)u.pm * tA; }
;     __device__ __forceinline__ long b_off(const Unit& u) const { return (long)u.pn * tB; }
;     __device__ __forceinline__ bool next(int i, Unit& u) const { u.z = i & 1; return o.tile(i >> 1, u); }
;     __device__ __forceinline__ long a_off(const Unit& u) const { return (long)u.pm * 256 * DM * 2 + (long)u.z * 512 * 2; }
;     __device__ __forceinline__ long b_off(const Unit& u) const { return ((long)u.z * 1024 + (long)u.pn * 256) * 512 * 2; }
;     __device__ __forceinline__ bool next(int i, Unit& u) const { u.z = 0; return o.tile(i, u); }
;     __device__ __forceinline__ long a_off(const Unit& u) const { const int ti = u.pm; const int b = ti / 65, i = ti % 65; return ((long)b * SEQ + 254 * i - 2) * DM * 2; }
;     __device__ __forceinline__ long b_off(const Unit& u) const { return (long)u.pn * 256 * DM * 2; }
; template <class Epi, class Sched>
; __device__ __forceinline__ void gemm_phase(LAS unsigned char* lds, const Gemm g, const Sched& S, const Epi& E) {
;     ...
;     for (;;) {
;         const bool has_next = S.next(ui + 1, nxt);
;         const char* nA = has_next ? (const char*)g.A + S.a_off(nxt) : cA; const char* nB = has_next ? (const char*)g.Bt + S.b_off(nxt) : cB;
;         for (int t = 0; t < nt; t += 2) {
;             const bool last = (t == nt - 2);
;             const char* a1 = cA + (size_t)(t + 1) * kstep;
;             const char* a2 = last ? nA : cA + (size_t)(t + 2) * kstep; const char* b2 = last ? nB : cB + (size_t)(t + 2) * kstep;
;     ...
; #pragma unroll
;         for (int a = 0; a < 2; ++a)
; #pragma unroll
;             for (int b = 0; b < 2; ++b)
; #pragma unroll
;                 for (int m = 0; m < 4; ++m)
; #pragma unroll
;                     for (int n = 0; n < 2; ++n) acc[a][b][m][n] = (f32x4){0.f, 0.f, 0.f, 0.f};
;         }
;         cur = nxt; cA = nA; cB = nB; ++ui;
.LBB0_173:
	s_ashr_i32 s15, s14, 31
	s_lshl_b64 s[16:17], s[14:15], 19
	s_add_u32 s16, s90, s16
	s_addc_u32 s17, s91, s17
	s_and_b64 s[18:19], s[40:41], exec
	s_cselect_b32 s15, s17, s21
	s_cselect_b32 s42, s16, s20
	s_ashr_i32 s13, s12, 31
	s_lshl_b64 s[18:19], s[12:13], 19
	v_readlane_b32 s13, v246, 16
	s_add_u32 s18, s13, s18
	v_readlane_b32 s13, v246, 17
	s_addc_u32 s19, s13, s19
	s_and_b64 s[22:23], s[40:41], exec
	s_cselect_b32 s13, s19, s1
	s_cselect_b32 s43, s18, s0
	s_add_u32 s51, s0, 0x100
	s_addc_u32 s54, s1, 0
	s_add_u32 s0, s20, 0x40080
	v_mov_b32_e32 v0, 0
	s_addc_u32 s1, s21, 0
	s_mov_b32 s55, -2
	v_mov_b32_e32 v1, v0
	v_mov_b32_e32 v2, v0
	v_mov_b32_e32 v3, v0
	v_mov_b32_e32 v4, v0
	v_mov_b32_e32 v5, v0
	v_mov_b32_e32 v6, v0
	v_mov_b32_e32 v7, v0
	v_mov_b32_e32 v16, v0
	v_mov_b32_e32 v17, v0
	v_mov_b32_e32 v18, v0
	v_mov_b32_e32 v19, v0
	v_mov_b32_e32 v20, v0
	v_mov_b32_e32 v21, v0
	v_mov_b32_e32 v22, v0
	v_mov_b32_e32 v23, v0
	v_mov_b32_e32 v36, v0
	v_mov_b32_e32 v37, v0
	v_mov_b32_e32 v38, v0
	v_mov_b32_e32 v39, v0
	v_mov_b32_e32 v48, v0
	v_mov_b32_e32 v49, v0
	v_mov_b32_e32 v50, v0
	v_mov_b32_e32 v51, v0
	v_mov_b32_e32 v64, v0
	v_mov_b32_e32 v65, v0
	v_mov_b32_e32 v66, v0
	v_mov_b32_e32 v67, v0
	v_mov_b32_e32 v68, v0
	v_mov_b32_e32 v69, v0
	v_mov_b32_e32 v70, v0
	v_mov_b32_e32 v71, v0
	v_mov_b32_e32 v8, v0
	v_mov_b32_e32 v9, v0
	v_mov_b32_e32 v10, v0
	v_mov_b32_e32 v11, v0
	v_mov_b32_e32 v12, v0
	v_mov_b32_e32 v13, v0
	v_mov_b32_e32 v14, v0
	v_mov_b32_e32 v15, v0
	v_mov_b32_e32 v24, v0
	v_mov_b32_e32 v25, v0
	v_mov_b32_e32 v26, v0
	v_mov_b32_e32 v27, v0
	v_mov_b32_e32 v28, v0
	v_mov_b32_e32 v29, v0
	v_mov_b32_e32 v30, v0
	v_mov_b32_e32 v31, v0
	v_mov_b32_e32 v56, v0
	v_mov_b32_e32 v57, v0
	v_mov_b32_e32 v58, v0
	v_mov_b32_e32 v59, v0
	v_mov_b32_e32 v60, v0
	v_mov_b32_e32 v61, v0
	v_mov_b32_e32 v62, v0
	v_mov_b32_e32 v63, v0
	v_mov_b32_e32 v72, v0
	v_mov_b32_e32 v73, v0
	v_mov_b32_e32 v74, v0
	v_mov_b32_e32 v75, v0
	v_mov_b32_e32 v76, v0
	v_mov_b32_e32 v77, v0
	v_mov_b32_e32 v78, v0
	v_mov_b32_e32 v79, v0
	v_mov_b32_e32 v80, v0
	v_mov_b32_e32 v81, v0
	v_mov_b32_e32 v82, v0
	v_mov_b32_e32 v83, v0
	v_mov_b32_e32 v84, v0
	v_mov_b32_e32 v85, v0
	v_mov_b32_e32 v86, v0
	v_mov_b32_e32 v87, v0
	v_mov_b32_e32 v98, v0
	v_mov_b32_e32 v99, v0
	v_mov_b32_e32 v100, v0
	v_mov_b32_e32 v101, v0
	v_mov_b32_e32 v102, v0
	v_mov_b32_e32 v103, v0
	v_mov_b32_e32 v104, v0
	v_mov_b32_e32 v105, v0
	v_mov_b32_e32 v114, v0
	v_mov_b32_e32 v115, v0
	v_mov_b32_e32 v116, v0
	v_mov_b32_e32 v117, v0
	v_mov_b32_e32 v118, v0
	v_mov_b32_e32 v119, v0
	v_mov_b32_e32 v120, v0
	v_mov_b32_e32 v121, v0
	v_mov_b32_e32 v130, v0
	v_mov_b32_e32 v131, v0
	v_mov_b32_e32 v132, v0
	v_mov_b32_e32 v133, v0
	v_mov_b32_e32 v134, v0
	v_mov_b32_e32 v135, v0
	v_mov_b32_e32 v136, v0
	v_mov_b32_e32 v137, v0
	v_mov_b32_e32 v88, v0
	v_mov_b32_e32 v89, v0
	v_mov_b32_e32 v90, v0
	v_mov_b32_e32 v91, v0
	v_mov_b32_e32 v92, v0
	v_mov_b32_e32 v93, v0
	v_mov_b32_e32 v94, v0
	v_mov_b32_e32 v95, v0
	v_mov_b32_e32 v106, v0
	v_mov_b32_e32 v107, v0
	v_mov_b32_e32 v108, v0
	v_mov_b32_e32 v109, v0
	v_mov_b32_e32 v110, v0
	v_mov_b32_e32 v111, v0
	v_mov_b32_e32 v112, v0
	v_mov_b32_e32 v113, v0
	v_mov_b32_e32 v122, v0
	v_mov_b32_e32 v123, v0
	v_mov_b32_e32 v124, v0
	v_mov_b32_e32 v125, v0
	v_mov_b32_e32 v126, v0
	v_mov_b32_e32 v127, v0
	v_mov_b32_e32 v128, v0
	v_mov_b32_e32 v129, v0
	v_mov_b32_e32 v138, v0
	v_mov_b32_e32 v139, v0
	v_mov_b32_e32 v140, v0
	v_mov_b32_e32 v141, v0
	v_mov_b32_e32 v142, v0
	v_mov_b32_e32 v143, v0
	v_mov_b32_e32 v144, v0
	v_mov_b32_e32 v145, v0
	s_nop 0
	s_nop 0
	s_nop 0
	s_nop 0
	s_nop 0
	s_nop 0
	s_nop 0
	s_nop 0
	s_nop 0
	s_nop 0
	s_nop 0
	s_nop 0

;     __device__ __forceinline__ bool next(int i, Unit& u) const { u.z = 0; return o.tile(i, u); }
;     __device__ __forceinline__ long a_off(const Unit& u) const { return (long)u.pm * tA; }
;     __device__ __forceinline__ long b_off(const Unit& u) const { return (long)u.pn * tB; }
;     __device__ __forceinline__ bool next(int i, Unit& u) const { u.z = 0; return o.tile(i, u); }
;     __device__ __forceinline__ long a_off(const Unit& u) const { const int ti = u.pm; const int b = ti / 65, i = ti % 65; return ((long)b * SEQ + 254 * i - 2) * DM * 2; }
;     __device__ __forceinline__ long b_off(const Unit& u) const { return (long)u.pn * 256 * DM * 2; }
; template <class Epi, class Sched>
; __device__ __forceinline__ void gemm_phase(LAS unsigned char* lds, const Gemm g, const Sched& S, const Epi& E) {
;     ...
;     for (;;) {
;         const bool has_next = S.next(ui + 1, nxt);
;         const char* nA = has_next ? (const char*)g.A + S.a_off(nxt) : cA; const char* nB = has_next ? (const char*)g.Bt + S.b_off(nxt) : cB;
;         for (int t = 0; t < nt; t += 2) {
;             const bool last = (t == nt - 2);
;             const char* a1 = cA + (size_t)(t + 1) * kstep;
;             const char* a2 = last ? nA : cA + (size_t)(t + 2) * kstep; const char* b2 = last ? nB : cB + (size_t)(t + 2) * kstep;
;             const char* a3 = a2 + kstep; const char* b3 = b2 + kstep;
;     __device__ __forceinline__ bool next(int i, Unit& u) const { u.z = i & 1; return o.tile(i >> 1, u); }
;     __device__ __forceinline__ long a_off(const Unit& u) const { return (long)u.pm * 256 * DM * 2 + (long)u.z * 512 * 2; }
;     __device__ __forceinline__ long b_off(const Unit& u) const { return ((long)u.z * 1024 + (long)u.pn * 256) * 512 * 2; }
.LBB0_726:
	s_and_b32 s70, s69, 1
	s_ashr_i32 s11, s10, 31
	s_lshl_b64 s[12:13], s[10:11], 19
	s_lshl_b32 s9, s70, 10
	s_add_u32 s11, s48, s12
	s_addc_u32 s13, s49, s13
	s_add_u32 s12, s11, s9
	s_addc_u32 s13, s13, 0
	s_and_b64 s[14:15], s[44:45], exec
	s_cselect_b32 s11, s13, s19
	s_cselect_b32 s72, s12, s18
	s_ashr_i32 s9, s8, 31
	s_lshl_b64 s[14:15], s[8:9], 18
	s_lshl_b32 s9, s70, 20
	s_add_u32 s14, s22, s14
	s_addc_u32 s15, s23, s15
	s_add_u32 s14, s14, s9
	s_addc_u32 s15, s15, 0
	s_and_b64 s[20:21], s[44:45], exec
	s_cselect_b32 s9, s15, s17
	s_cselect_b32 s73, s14, s16
	s_add_u32 s74, s16, 0x100
	s_addc_u32 s75, s17, 0
	s_add_u32 s16, s18, 0x40080
	s_addc_u32 s17, s19, 0
	s_mov_b32 s76, -2
	s_nop 0
	s_nop 0
	s_nop 0
	s_nop 0
	s_nop 0
	s_nop 0
	s_nop 0
	s_nop 0
	s_nop 0
	s_nop 0

;     __device__ __forceinline__ bool next(int i, Unit& u) const { u.z = 0; return o.tile(i, u); }
;     __device__ __forceinline__ long a_off(const Unit& u) const { return (long)u.pm * tA; }
;     __device__ __forceinline__ long b_off(const Unit& u) const { return (long)u.pn * tB; }
;     __device__ __forceinline__ bool next(int i, Unit& u) const { u.z = i & 1; return o.tile(i >> 1, u); }
;     __device__ __forceinline__ long a_off(const Unit& u) const { return (long)u.pm * 256 * DM * 2 + (long)u.z * 512 * 2; }
;     __device__ __forceinline__ long b_off(const Unit& u) const { return ((long)u.z * 1024 + (long)u.pn * 256) * 512 * 2; }
;     __device__ __forceinline__ bool next(int i, Unit& u) const { u.z = 0; return o.tile(i, u); }
;     __device__ __forceinline__ long a_off(const Unit& u) const { const int ti = u.pm; const int b = ti / 65, i = ti % 65; return ((long)b * SEQ + 254 * i - 2) * DM * 2; }
;     __device__ __forceinline__ long b_off(const Unit& u) const { return (long)u.pn * 256 * DM * 2; }
; template <class Epi, class Sched>
; __device__ __forceinline__ void gemm_phase(LAS unsigned char* lds, const Gemm g, const Sched& S, const Epi& E) {
;     ...
;     for (;;) {
;         const bool has_next = S.next(ui + 1, nxt);
;         const char* nA = has_next ? (const char*)g.A + S.a_off(nxt) : cA; const char* nB = has_next ? (const char*)g.Bt + S.b_off(nxt) : cB;
;         for (int t = 0; t < nt; t += 2) {
;             const bool last = (t == nt - 2);
;             const char* a1 = cA + (size_t)(t + 1) * kstep;
;             const char* a2 = last ? nA : cA + (size_t)(t + 2) * kstep; const char* b2 = last ? nB : cB + (size_t)(t + 2) * kstep;
;     ...
; #pragma unroll
;         for (int a = 0; a < 2; ++a)
; #pragma unroll
;             for (int b = 0; b < 2; ++b)
; #pragma unroll
;                 for (int m = 0; m < 4; ++m)
; #pragma unroll
;                     for (int n = 0; n < 2; ++n) acc[a][b][m][n] = (f32x4){0.f, 0.f, 0.f, 0.f};
;         }
;         cur = nxt; cA = nA; cB = nB; ++ui;
.LBB0_878:
	s_ashr_i32 s15, s14, 31
	s_lshl_b64 s[16:17], s[14:15], 19
	s_add_u32 s16, s54, s16
	s_addc_u32 s17, s55, s17
	s_and_b64 s[18:19], s[46:47], exec
	s_cselect_b32 s15, s17, s21
	s_cselect_b32 s49, s16, s20
	s_ashr_i32 s13, s12, 31
	s_lshl_b64 s[18:19], s[12:13], 19
	s_add_u32 s18, s40, s18
	s_addc_u32 s19, s41, s19
	s_and_b64 s[22:23], s[46:47], exec
	s_cselect_b32 s13, s19, s1
	s_cselect_b32 s50, s18, s0
	s_add_u32 s51, s0, 0x100
	s_addc_u32 s56, s1, 0
	s_add_u32 s0, s20, 0x40080
	v_mov_b32_e32 v0, 0
	s_addc_u32 s1, s21, 0
	s_mov_b32 s57, -2
	s_waitcnt lgkmcnt(0)
	v_mov_b32_e32 v1, v0
	v_mov_b32_e32 v2, v0
	v_mov_b32_e32 v3, v0
	v_mov_b32_e32 v4, v0
	v_mov_b32_e32 v5, v0
	v_mov_b32_e32 v6, v0
	v_mov_b32_e32 v7, v0
	v_mov_b32_e32 v16, v0
	v_mov_b32_e32 v17, v0
	v_mov_b32_e32 v18, v0
	v_mov_b32_e32 v19, v0
	v_mov_b32_e32 v20, v0
	v_mov_b32_e32 v21, v0
	v_mov_b32_e32 v22, v0
	v_mov_b32_e32 v23, v0
	v_mov_b32_e32 v32, v0
	v_mov_b32_e32 v33, v0
	v_mov_b32_e32 v34, v0
	v_mov_b32_e32 v35, v0
	v_mov_b32_e32 v36, v0
	v_mov_b32_e32 v37, v0
	v_mov_b32_e32 v38, v0
	v_mov_b32_e32 v39, v0
	v_mov_b32_e32 v48, v0
	v_mov_b32_e32 v49, v0
	v_mov_b32_e32 v50, v0
	v_mov_b32_e32 v51, v0
	v_mov_b32_e32 v52, v0
	v_mov_b32_e32 v53, v0
	v_mov_b32_e32 v54, v0
	v_mov_b32_e32 v55, v0
	v_mov_b32_e32 v8, v0
	v_mov_b32_e32 v9, v0
	v_mov_b32_e32 v10, v0
	v_mov_b32_e32 v11, v0
	v_mov_b32_e32 v12, v0
	v_mov_b32_e32 v13, v0
	v_mov_b32_e32 v14, v0
	v_mov_b32_e32 v15, v0
	v_mov_b32_e32 v24, v0
	v_mov_b32_e32 v25, v0
	v_mov_b32_e32 v26, v0
	v_mov_b32_e32 v27, v0
	v_mov_b32_e32 v28, v0
	v_mov_b32_e32 v29, v0
	v_mov_b32_e32 v30, v0
	v_mov_b32_e32 v31, v0
	v_mov_b32_e32 v40, v0
	v_mov_b32_e32 v41, v0
	v_mov_b32_e32 v42, v0
	v_mov_b32_e32 v43, v0
	v_mov_b32_e32 v44, v0
	v_mov_b32_e32 v45, v0
	v_mov_b32_e32 v46, v0
	v_mov_b32_e32 v47, v0
	v_mov_b32_e32 v56, v0
	v_mov_b32_e32 v57, v0
	v_mov_b32_e32 v58, v0
	v_mov_b32_e32 v59, v0
	v_mov_b32_e32 v60, v0
	v_mov_b32_e32 v61, v0
	v_mov_b32_e32 v62, v0
	v_mov_b32_e32 v63, v0
	v_mov_b32_e32 v64, v0
	v_mov_b32_e32 v65, v0
	v_mov_b32_e32 v66, v0
	v_mov_b32_e32 v67, v0
	v_mov_b32_e32 v68, v0
	v_mov_b32_e32 v69, v0
	v_mov_b32_e32 v70, v0
	v_mov_b32_e32 v71, v0
	v_mov_b32_e32 v80, v0
	v_mov_b32_e32 v81, v0
	v_mov_b32_e32 v82, v0
	v_mov_b32_e32 v83, v0
	v_mov_b32_e32 v84, v0
	v_mov_b32_e32 v85, v0
	v_mov_b32_e32 v86, v0
	v_mov_b32_e32 v87, v0
	v_mov_b32_e32 v98, v0
	v_mov_b32_e32 v99, v0
	v_mov_b32_e32 v100, v0
	v_mov_b32_e32 v101, v0
	v_mov_b32_e32 v102, v0
	v_mov_b32_e32 v103, v0
	v_mov_b32_e32 v104, v0
	v_mov_b32_e32 v105, v0
	v_mov_b32_e32 v114, v0
	v_mov_b32_e32 v115, v0
	v_mov_b32_e32 v116, v0
	v_mov_b32_e32 v117, v0
	v_mov_b32_e32 v122, v0
	v_mov_b32_e32 v123, v0
	v_mov_b32_e32 v124, v0
	v_mov_b32_e32 v125, v0
	v_mov_b32_e32 v72, v0
	v_mov_b32_e32 v73, v0
	v_mov_b32_e32 v74, v0
	v_mov_b32_e32 v75, v0
	v_mov_b32_e32 v76, v0
	v_mov_b32_e32 v77, v0
	v_mov_b32_e32 v78, v0
	v_mov_b32_e32 v79, v0
	v_mov_b32_e32 v88, v0
	v_mov_b32_e32 v89, v0
	v_mov_b32_e32 v90, v0
	v_mov_b32_e32 v91, v0
	v_mov_b32_e32 v92, v0
	v_mov_b32_e32 v93, v0
	v_mov_b32_e32 v94, v0
	v_mov_b32_e32 v95, v0
	v_mov_b32_e32 v106, v0
	v_mov_b32_e32 v107, v0
	v_mov_b32_e32 v108, v0
	v_mov_b32_e32 v109, v0
	v_mov_b32_e32 v110, v0
	v_mov_b32_e32 v111, v0
	v_mov_b32_e32 v112, v0
	v_mov_b32_e32 v113, v0
	v_mov_b32_e32 v130, v0
	v_mov_b32_e32 v131, v0
	v_mov_b32_e32 v132, v0
	v_mov_b32_e32 v133, v0
	v_mov_b32_e32 v142, v0
	v_mov_b32_e32 v143, v0
	v_mov_b32_e32 v144, v0
	v_mov_b32_e32 v145, v0
	s_nop 0
	s_nop 0
	s_nop 0
	s_nop 0

;     __device__ __forceinline__ bool next(int i, Unit& u) const { u.z = 0; return o.tile(i, u); }
;     __device__ __forceinline__ long a_off(const Unit& u) const { return (long)u.pm * tA; }
;     __device__ __forceinline__ long b_off(const Unit& u) const { return (long)u.pn * tB; }
;     __device__ __forceinline__ bool next(int i, Unit& u) const { u.z = i & 1; return o.tile(i >> 1, u); }
;     __device__ __forceinline__ long a_off(const Unit& u) const { return (long)u.pm * 256 * DM * 2 + (long)u.z * 512 * 2; }
;     __device__ __forceinline__ long b_off(const Unit& u) const { return ((long)u.z * 1024 + (long)u.pn * 256) * 512 * 2; }
;     __device__ __forceinline__ bool next(int i, Unit& u) const { u.z = 0; return o.tile(i, u); }
;     __device__ __forceinline__ long a_off(const Unit& u) const { const int ti = u.pm; const int b = ti / 65, i = ti % 65; return ((long)b * SEQ + 254 * i - 2) * DM * 2; }
;     __device__ __forceinline__ long b_off(const Unit& u) const { return (long)u.pn * 256 * DM * 2; }
; template <class Epi, class Sched>
; __device__ __forceinline__ void gemm_phase(LAS unsigned char* lds, const Gemm g, const Sched& S, const Epi& E) {
;     ...
;     for (;;) {
;         const bool has_next = S.next(ui + 1, nxt);
;         const char* nA = has_next ? (const char*)g.A + S.a_off(nxt) : cA; const char* nB = has_next ? (const char*)g.Bt + S.b_off(nxt) : cB;
;         for (int t = 0; t < nt; t += 2) {
;             const bool last = (t == nt - 2);
;             const char* a1 = cA + (size_t)(t + 1) * kstep;
;             const char* a2 = last ? nA : cA + (size_t)(t + 2) * kstep; const char* b2 = last ? nB : cB + (size_t)(t + 2) * kstep;
;     ...
; #pragma unroll
;         for (int a = 0; a < 2; ++a)
; #pragma unroll
;             for (int b = 0; b < 2; ++b)
; #pragma unroll
;                 for (int m = 0; m < 4; ++m)
; #pragma unroll
;                     for (int n = 0; n < 2; ++n) acc[a][b][m][n] = (f32x4){0.f, 0.f, 0.f, 0.f};
;         }
;         cur = nxt; cA = nA; cB = nB; ++ui;
.LBB0_923:
	s_ashr_i32 s15, s14, 31
	s_lshl_b64 s[16:17], s[14:15], 19
	s_add_u32 s16, s54, s16
	s_addc_u32 s17, s55, s17
	s_and_b64 s[18:19], s[46:47], exec
	s_cselect_b32 s15, s17, s21
	s_cselect_b32 s49, s16, s20
	s_ashr_i32 s13, s12, 31
	s_lshl_b64 s[18:19], s[12:13], 19
	s_add_u32 s18, s40, s18
	s_addc_u32 s19, s41, s19
	s_and_b64 s[22:23], s[46:47], exec
	s_cselect_b32 s13, s19, s1
	s_cselect_b32 s50, s18, s0
	s_add_u32 s51, s0, 0x100
	s_addc_u32 s56, s1, 0
	s_add_u32 s0, s20, 0x40080
	v_mov_b32_e32 v0, 0
	s_addc_u32 s1, s21, 0
	s_mov_b32 s57, -2
	s_waitcnt lgkmcnt(0)
	v_mov_b32_e32 v1, v0
	v_mov_b32_e32 v2, v0
	v_mov_b32_e32 v3, v0
	v_mov_b32_e32 v4, v0
	v_mov_b32_e32 v5, v0
	v_mov_b32_e32 v6, v0
	v_mov_b32_e32 v7, v0
	v_mov_b32_e32 v16, v0
	v_mov_b32_e32 v17, v0
	v_mov_b32_e32 v18, v0
	v_mov_b32_e32 v19, v0
	v_mov_b32_e32 v20, v0
	v_mov_b32_e32 v21, v0
	v_mov_b32_e32 v22, v0
	v_mov_b32_e32 v23, v0
	v_mov_b32_e32 v32, v0
	v_mov_b32_e32 v33, v0
	v_mov_b32_e32 v34, v0
	v_mov_b32_e32 v35, v0
	v_mov_b32_e32 v36, v0
	v_mov_b32_e32 v37, v0
	v_mov_b32_e32 v38, v0
	v_mov_b32_e32 v39, v0
	v_mov_b32_e32 v48, v0
	v_mov_b32_e32 v49, v0
	v_mov_b32_e32 v50, v0
	v_mov_b32_e32 v51, v0
	v_mov_b32_e32 v52, v0
	v_mov_b32_e32 v53, v0
	v_mov_b32_e32 v54, v0
	v_mov_b32_e32 v55, v0
	v_mov_b32_e32 v8, v0
	v_mov_b32_e32 v9, v0
	v_mov_b32_e32 v10, v0
	v_mov_b32_e32 v11, v0
	v_mov_b32_e32 v12, v0
	v_mov_b32_e32 v13, v0
	v_mov_b32_e32 v14, v0
	v_mov_b32_e32 v15, v0
	v_mov_b32_e32 v24, v0
	v_mov_b32_e32 v25, v0
	v_mov_b32_e32 v26, v0
	v_mov_b32_e32 v27, v0
	v_mov_b32_e32 v28, v0
	v_mov_b32_e32 v29, v0
	v_mov_b32_e32 v30, v0
	v_mov_b32_e32 v31, v0
	v_mov_b32_e32 v40, v0
	v_mov_b32_e32 v41, v0
	v_mov_b32_e32 v42, v0
	v_mov_b32_e32 v43, v0
	v_mov_b32_e32 v44, v0
	v_mov_b32_e32 v45, v0
	v_mov_b32_e32 v46, v0
	v_mov_b32_e32 v47, v0
	v_mov_b32_e32 v56, v0
	v_mov_b32_e32 v57, v0
	v_mov_b32_e32 v58, v0
	v_mov_b32_e32 v59, v0
	v_mov_b32_e32 v60, v0
	v_mov_b32_e32 v61, v0
	v_mov_b32_e32 v62, v0
	v_mov_b32_e32 v63, v0
	v_mov_b32_e32 v64, v0
	v_mov_b32_e32 v65, v0
	v_mov_b32_e32 v66, v0
	v_mov_b32_e32 v67, v0
	v_mov_b32_e32 v68, v0
	v_mov_b32_e32 v69, v0
	v_mov_b32_e32 v70, v0
	v_mov_b32_e32 v71, v0
	v_mov_b32_e32 v80, v0
	v_mov_b32_e32 v81, v0
	v_mov_b32_e32 v82, v0
	v_mov_b32_e32 v83, v0
	v_mov_b32_e32 v84, v0
	v_mov_b32_e32 v85, v0
	v_mov_b32_e32 v86, v0
	v_mov_b32_e32 v87, v0
	v_mov_b32_e32 v98, v0
	v_mov_b32_e32 v99, v0
	v_mov_b32_e32 v100, v0
	v_mov_b32_e32 v101, v0
	v_mov_b32_e32 v102, v0
	v_mov_b32_e32 v103, v0
	v_mov_b32_e32 v104, v0
	v_mov_b32_e32 v105, v0
	v_mov_b32_e32 v114, v0
	v_mov_b32_e32 v115, v0
	v_mov_b32_e32 v116, v0
	v_mov_b32_e32 v117, v0
	v_mov_b32_e32 v118, v0
	v_mov_b32_e32 v119, v0
	v_mov_b32_e32 v120, v0
	v_mov_b32_e32 v121, v0
	v_mov_b32_e32 v72, v0
	v_mov_b32_e32 v73, v0
	v_mov_b32_e32 v74, v0
	v_mov_b32_e32 v75, v0
	v_mov_b32_e32 v76, v0
	v_mov_b32_e32 v77, v0
	v_mov_b32_e32 v78, v0
	v_mov_b32_e32 v79, v0
	v_mov_b32_e32 v88, v0
	v_mov_b32_e32 v89, v0
	v_mov_b32_e32 v90, v0
	v_mov_b32_e32 v91, v0
	v_mov_b32_e32 v92, v0
	v_mov_b32_e32 v93, v0
	v_mov_b32_e32 v94, v0
	v_mov_b32_e32 v95, v0
	v_mov_b32_e32 v106, v0
	v_mov_b32_e32 v107, v0
	v_mov_b32_e32 v108, v0
	v_mov_b32_e32 v109, v0
	v_mov_b32_e32 v110, v0
	v_mov_b32_e32 v111, v0
	v_mov_b32_e32 v112, v0
	v_mov_b32_e32 v113, v0
	v_mov_b32_e32 v122, v0
	v_mov_b32_e32 v123, v0
	v_mov_b32_e32 v124, v0
	v_mov_b32_e32 v125, v0
	v_mov_b32_e32 v126, v0
	v_mov_b32_e32 v127, v0
	v_mov_b32_e32 v128, v0
	v_mov_b32_e32 v129, v0
	s_nop 0
	s_nop 0
	s_nop 0
	s_nop 0
	s_nop 0

;     __device__ __forceinline__ bool next(int i, Unit& u) const { u.z = 0; return o.tile(i, u); }
;     __device__ __forceinline__ long a_off(const Unit& u) const { return (long)u.pm * tA; }
;     __device__ __forceinline__ long b_off(const Unit& u) const { return (long)u.pn * tB; }
;     __device__ __forceinline__ bool next(int i, Unit& u) const { u.z = i & 1; return o.tile(i >> 1, u); }
;     __device__ __forceinline__ long a_off(const Unit& u) const { return (long)u.pm * 256 * DM * 2 + (long)u.z * 512 * 2; }
;     __device__ __forceinline__ long b_off(const Unit& u) const { return ((long)u.z * 1024 + (long)u.pn * 256) * 512 * 2; }
;     __device__ __forceinline__ bool next(int i, Unit& u) const { u.z = 0; return o.tile(i, u); }
;     __device__ __forceinline__ long a_off(const Unit& u) const { const int ti = u.pm; const int b = ti / 65, i = ti % 65; return ((long)b * SEQ + 254 * i - 2) * DM * 2; }
;     __device__ __forceinline__ long b_off(const Unit& u) const { return (long)u.pn * 256 * DM * 2; }
; template <class Epi, class Sched>
; __device__ __forceinline__ void gemm_phase(LAS unsigned char* lds, const Gemm g, const Sched& S, const Epi& E) {
;     ...
;     for (;;) {
;         const bool has_next = S.next(ui + 1, nxt);
;         const char* nA = has_next ? (const char*)g.A + S.a_off(nxt) : cA; const char* nB = has_next ? (const char*)g.Bt + S.b_off(nxt) : cB;
;         for (int t = 0; t < nt; t += 2) {
;             const bool last = (t == nt - 2);
;             const char* a1 = cA + (size_t)(t + 1) * kstep;
;             const char* a2 = last ? nA : cA + (size_t)(t + 2) * kstep; const char* b2 = last ? nB : cB + (size_t)(t + 2) * kstep;
;     ...
; #pragma unroll
;         for (int a = 0; a < 2; ++a)
; #pragma unroll
;             for (int b = 0; b < 2; ++b)
; #pragma unroll
;                 for (int m = 0; m < 4; ++m)
; #pragma unroll
;                     for (int n = 0; n < 2; ++n) acc[a][b][m][n] = (f32x4){0.f, 0.f, 0.f, 0.f};
;         }
;         cur = nxt; cA = nA; cB = nB; ++ui;
.LBB0_1024:
	s_ashr_i32 s9, s8, 31
	s_lshl_b64 s[10:11], s[8:9], 19
	s_add_u32 s10, s90, s10
	s_addc_u32 s11, s91, s11
	s_and_b64 s[12:13], s[46:47], exec
	s_cselect_b32 s9, s11, s19
	s_cselect_b32 s17, s10, s18
	s_ashr_i32 s3, s2, 31
	s_lshl_b64 s[12:13], s[2:3], 19
	v_readlane_b32 s3, v246, 26
	s_add_u32 s12, s3, s12
	v_readlane_b32 s3, v246, 27
	s_addc_u32 s13, s3, s13
	s_and_b64 s[20:21], s[46:47], exec
	s_cselect_b32 s3, s13, s15
	s_cselect_b32 s23, s12, s14
	s_add_u32 s48, s14, 0x100
	s_addc_u32 s49, s15, 0
	s_add_u32 s14, s18, 0x40080
	v_mov_b32_e32 v20, 0
	s_addc_u32 s15, s19, 0
	s_mov_b32 s50, -2
	v_mov_b32_e32 v21, v20
	v_mov_b32_e32 v22, v20
	v_mov_b32_e32 v23, v20
	v_mov_b32_e32 v128, v20
	v_mov_b32_e32 v129, v20
	v_mov_b32_e32 v130, v20
	v_mov_b32_e32 v131, v20
	v_mov_b32_e32 v0, v20
	v_mov_b32_e32 v1, v20
	v_mov_b32_e32 v2, v20
	v_mov_b32_e32 v3, v20
	v_mov_b32_e32 v64, v20
	v_mov_b32_e32 v65, v20
	v_mov_b32_e32 v66, v20
	v_mov_b32_e32 v67, v20
	v_mov_b32_e32 v8, v20
	v_mov_b32_e32 v9, v20
	v_mov_b32_e32 v10, v20
	v_mov_b32_e32 v11, v20
	v_mov_b32_e32 v72, v20
	v_mov_b32_e32 v73, v20
	v_mov_b32_e32 v74, v20
	v_mov_b32_e32 v75, v20
	v_mov_b32_e32 v24, v20
	v_mov_b32_e32 v25, v20
	v_mov_b32_e32 v26, v20
	v_mov_b32_e32 v27, v20
	v_mov_b32_e32 v132, v20
	v_mov_b32_e32 v133, v20
	v_mov_b32_e32 v134, v20
	v_mov_b32_e32 v135, v20
	v_mov_b32_e32 v16, v20
	v_mov_b32_e32 v17, v20
	v_mov_b32_e32 v18, v20
	v_mov_b32_e32 v19, v20
	v_mov_b32_e32 v122, v20
	v_mov_b32_e32 v123, v20
	v_mov_b32_e32 v124, v20
	v_mov_b32_e32 v125, v20
	v_mov_b32_e32 v4, v20
	v_mov_b32_e32 v5, v20
	v_mov_b32_e32 v6, v20
	v_mov_b32_e32 v7, v20
	v_mov_b32_e32 v68, v20
	v_mov_b32_e32 v69, v20
	v_mov_b32_e32 v70, v20
	v_mov_b32_e32 v71, v20
	v_mov_b32_e32 v12, v20
	v_mov_b32_e32 v13, v20
	v_mov_b32_e32 v14, v20
	v_mov_b32_e32 v15, v20
	v_mov_b32_e32 v76, v20
	v_mov_b32_e32 v77, v20
	v_mov_b32_e32 v78, v20
	v_mov_b32_e32 v79, v20
	v_mov_b32_e32 v28, v20
	v_mov_b32_e32 v29, v20
	v_mov_b32_e32 v30, v20
	v_mov_b32_e32 v31, v20
	v_mov_b32_e32 v136, v20
	v_mov_b32_e32 v137, v20
	v_mov_b32_e32 v138, v20
	v_mov_b32_e32 v139, v20
	v_mov_b32_e32 v44, v20
	v_mov_b32_e32 v45, v20
	v_mov_b32_e32 v46, v20
	v_mov_b32_e32 v47, v20
	v_mov_b32_e32 v148, v20
	v_mov_b32_e32 v149, v20
	v_mov_b32_e32 v150, v20
	v_mov_b32_e32 v151, v20
	v_mov_b32_e32 v32, v20
	v_mov_b32_e32 v33, v20
	v_mov_b32_e32 v34, v20
	v_mov_b32_e32 v35, v20
	v_mov_b32_e32 v114, v20
	v_mov_b32_e32 v115, v20
	v_mov_b32_e32 v116, v20
	v_mov_b32_e32 v117, v20
	v_mov_b32_e32 v40, v20
	v_mov_b32_e32 v41, v20
	v_mov_b32_e32 v42, v20
	v_mov_b32_e32 v43, v20
	v_mov_b32_e32 v118, v20
	v_mov_b32_e32 v119, v20
	v_mov_b32_e32 v120, v20
	v_mov_b32_e32 v121, v20
	v_mov_b32_e32 v56, v20
	v_mov_b32_e32 v57, v20
	v_mov_b32_e32 v58, v20
	v_mov_b32_e32 v59, v20
	v_mov_b32_e32 v156, v20
	v_mov_b32_e32 v157, v20
	v_mov_b32_e32 v158, v20
	v_mov_b32_e32 v159, v20
	v_mov_b32_e32 v48, v20
	v_mov_b32_e32 v49, v20
	v_mov_b32_e32 v50, v20
	v_mov_b32_e32 v51, v20
	v_mov_b32_e32 v152, v20
	v_mov_b32_e32 v153, v20
	v_mov_b32_e32 v154, v20
	v_mov_b32_e32 v155, v20
	v_mov_b32_e32 v36, v20
	v_mov_b32_e32 v37, v20
	v_mov_b32_e32 v38, v20
	v_mov_b32_e32 v39, v20
	v_mov_b32_e32 v140, v20
	v_mov_b32_e32 v141, v20
	v_mov_b32_e32 v142, v20
	v_mov_b32_e32 v143, v20
	v_mov_b32_e32 v52, v20
	v_mov_b32_e32 v53, v20
	v_mov_b32_e32 v54, v20
	v_mov_b32_e32 v55, v20
	v_mov_b32_e32 v144, v20
	v_mov_b32_e32 v145, v20
	v_mov_b32_e32 v146, v20
	v_mov_b32_e32 v147, v20
	v_mov_b32_e32 v60, v20
	v_mov_b32_e32 v61, v20
	v_mov_b32_e32 v62, v20
	v_mov_b32_e32 v63, v20
	v_mov_b32_e32 v160, v20
	v_mov_b32_e32 v161, v20
	v_mov_b32_e32 v162, v20
	v_mov_b32_e32 v163, v20
	s_nop 0
	s_nop 0

;     __device__ __forceinline__ bool next(int i, Unit& u) const { u.z = 0; return o.tile(i, u); }
;     __device__ __forceinline__ long a_off(const Unit& u) const { return (long)u.pm * tA; }
;     __device__ __forceinline__ long b_off(const Unit& u) const { return (long)u.pn * tB; }
;     __device__ __forceinline__ bool next(int i, Unit& u) const { u.z = i & 1; return o.tile(i >> 1, u); }
;     __device__ __forceinline__ long a_off(const Unit& u) const { return (long)u.pm * 256 * DM * 2 + (long)u.z * 512 * 2; }
;     __device__ __forceinline__ long b_off(const Unit& u) const { return ((long)u.z * 1024 + (long)u.pn * 256) * 512 * 2; }
;     __device__ __forceinline__ bool next(int i, Unit& u) const { u.z = 0; return o.tile(i, u); }
;     __device__ __forceinline__ long a_off(const Unit& u) const { const int ti = u.pm; const int b = ti / 65, i = ti % 65; return ((long)b * SEQ + 254 * i - 2) * DM * 2; }
;     __device__ __forceinline__ long b_off(const Unit& u) const { return (long)u.pn * 256 * DM * 2; }
; template <class Epi, class Sched>
; __device__ __forceinline__ void gemm_phase(LAS unsigned char* lds, const Gemm g, const Sched& S, const Epi& E) {
;     ...
;     for (;;) {
;         const bool has_next = S.next(ui + 1, nxt);
;         const char* nA = has_next ? (const char*)g.A + S.a_off(nxt) : cA; const char* nB = has_next ? (const char*)g.Bt + S.b_off(nxt) : cB;
;         for (int t = 0; t < nt; t += 2) {
;             const bool last = (t == nt - 2);
;             const char* a1 = cA + (size_t)(t + 1) * kstep;
;             const char* a2 = last ? nA : cA + (size_t)(t + 2) * kstep; const char* b2 = last ? nB : cB + (size_t)(t + 2) * kstep;
;     ...
; #pragma unroll
;         for (int a = 0; a < 2; ++a)
; #pragma unroll
;             for (int b = 0; b < 2; ++b)
; #pragma unroll
;                 for (int m = 0; m < 4; ++m)
; #pragma unroll
;                     for (int n = 0; n < 2; ++n) acc[a][b][m][n] = (f32x4){0.f, 0.f, 0.f, 0.f};
;         }
;         cur = nxt; cA = nA; cB = nB; ++ui;
.LBB0_1241:
	s_add_u32 s45, s14, 0x100
	v_mov_b32_e32 v0, 0
	s_addc_u32 s48, s15, 0
	s_mov_b32 s49, -2
	v_mov_b32_e32 v1, v0
	v_mov_b32_e32 v2, v0
	v_mov_b32_e32 v3, v0
	v_mov_b32_e32 v4, v0
	v_mov_b32_e32 v5, v0
	v_mov_b32_e32 v6, v0
	v_mov_b32_e32 v7, v0
	v_mov_b32_e32 v12, v0
	v_mov_b32_e32 v13, v0
	v_mov_b32_e32 v14, v0
	v_mov_b32_e32 v15, v0
	v_mov_b32_e32 v20, v0
	v_mov_b32_e32 v21, v0
	v_mov_b32_e32 v22, v0
	v_mov_b32_e32 v23, v0
	v_mov_b32_e32 v28, v0
	v_mov_b32_e32 v29, v0
	v_mov_b32_e32 v30, v0
	v_mov_b32_e32 v31, v0
	v_mov_b32_e32 v36, v0
	v_mov_b32_e32 v37, v0
	v_mov_b32_e32 v38, v0
	v_mov_b32_e32 v39, v0
	v_mov_b32_e32 v44, v0
	v_mov_b32_e32 v45, v0
	v_mov_b32_e32 v46, v0
	v_mov_b32_e32 v47, v0
	v_mov_b32_e32 v52, v0
	v_mov_b32_e32 v53, v0
	v_mov_b32_e32 v54, v0
	v_mov_b32_e32 v55, v0
	v_mov_b32_e32 v8, v0
	v_mov_b32_e32 v9, v0
	v_mov_b32_e32 v10, v0
	v_mov_b32_e32 v11, v0
	v_mov_b32_e32 v16, v0
	v_mov_b32_e32 v17, v0
	v_mov_b32_e32 v18, v0
	v_mov_b32_e32 v19, v0
	v_mov_b32_e32 v24, v0
	v_mov_b32_e32 v25, v0
	v_mov_b32_e32 v26, v0
	v_mov_b32_e32 v27, v0
	v_mov_b32_e32 v32, v0
	v_mov_b32_e32 v33, v0
	v_mov_b32_e32 v34, v0
	v_mov_b32_e32 v35, v0
	v_mov_b32_e32 v40, v0
	v_mov_b32_e32 v41, v0
	v_mov_b32_e32 v42, v0
	v_mov_b32_e32 v43, v0
	v_mov_b32_e32 v48, v0
	v_mov_b32_e32 v49, v0
	v_mov_b32_e32 v50, v0
	v_mov_b32_e32 v51, v0
	v_mov_b32_e32 v56, v0
	v_mov_b32_e32 v57, v0
	v_mov_b32_e32 v58, v0
	v_mov_b32_e32 v59, v0
	v_mov_b32_e32 v60, v0
	v_mov_b32_e32 v61, v0
	v_mov_b32_e32 v62, v0
	v_mov_b32_e32 v63, v0
	v_mov_b32_e32 v64, v0
	v_mov_b32_e32 v65, v0
	v_mov_b32_e32 v66, v0
	v_mov_b32_e32 v67, v0
	v_mov_b32_e32 v68, v0
	v_mov_b32_e32 v69, v0
	v_mov_b32_e32 v70, v0
	v_mov_b32_e32 v71, v0
	v_mov_b32_e32 v76, v0
	v_mov_b32_e32 v77, v0
	v_mov_b32_e32 v78, v0
	v_mov_b32_e32 v79, v0
	v_mov_b32_e32 v84, v0
	v_mov_b32_e32 v85, v0
	v_mov_b32_e32 v86, v0
	v_mov_b32_e32 v87, v0
	v_mov_b32_e32 v92, v0
	v_mov_b32_e32 v93, v0
	v_mov_b32_e32 v94, v0
	v_mov_b32_e32 v95, v0
	v_mov_b32_e32 v102, v0
	v_mov_b32_e32 v103, v0
	v_mov_b32_e32 v104, v0
	v_mov_b32_e32 v105, v0
	v_mov_b32_e32 v110, v0
	v_mov_b32_e32 v111, v0
	v_mov_b32_e32 v112, v0
	v_mov_b32_e32 v113, v0
	v_mov_b32_e32 v118, v0
	v_mov_b32_e32 v119, v0
	v_mov_b32_e32 v120, v0
	v_mov_b32_e32 v121, v0
	v_mov_b32_e32 v72, v0
	v_mov_b32_e32 v73, v0
	v_mov_b32_e32 v74, v0
	v_mov_b32_e32 v75, v0
	v_mov_b32_e32 v80, v0
	v_mov_b32_e32 v81, v0
	v_mov_b32_e32 v82, v0
	v_mov_b32_e32 v83, v0
	v_mov_b32_e32 v88, v0
	v_mov_b32_e32 v89, v0
	v_mov_b32_e32 v90, v0
	v_mov_b32_e32 v91, v0
	v_mov_b32_e32 v98, v0
	v_mov_b32_e32 v99, v0
	v_mov_b32_e32 v100, v0
	v_mov_b32_e32 v101, v0
	v_mov_b32_e32 v106, v0
	v_mov_b32_e32 v107, v0
	v_mov_b32_e32 v108, v0
	v_mov_b32_e32 v109, v0
	v_mov_b32_e32 v114, v0
	v_mov_b32_e32 v115, v0
	v_mov_b32_e32 v116, v0
	v_mov_b32_e32 v117, v0
	v_mov_b32_e32 v122, v0
	v_mov_b32_e32 v123, v0
	v_mov_b32_e32 v124, v0
	v_mov_b32_e32 v125, v0
	v_mov_b32_e32 v126, v0
	v_mov_b32_e32 v127, v0
	v_mov_b32_e32 v128, v0
	v_mov_b32_e32 v129, v0
	s_nop 0
	s_nop 0
	s_nop 0

;     __device__ __forceinline__ bool next(int i, Unit& u) const { u.z = 0; return o.tile(i, u); }
;     __device__ __forceinline__ long a_off(const Unit& u) const { return (long)u.pm * tA; }
;     __device__ __forceinline__ long b_off(const Unit& u) const { return (long)u.pn * tB; }
;     __device__ __forceinline__ bool next(int i, Unit& u) const { u.z = i & 1; return o.tile(i >> 1, u); }
;     __device__ __forceinline__ long a_off(const Unit& u) const { return (long)u.pm * 256 * DM * 2 + (long)u.z * 512 * 2; }
;     __device__ __forceinline__ long b_off(const Unit& u) const { return ((long)u.z * 1024 + (long)u.pn * 256) * 512 * 2; }
;     __device__ __forceinline__ bool next(int i, Unit& u) const { u.z = 0; return o.tile(i, u); }
;     __device__ __forceinline__ long a_off(const Unit& u) const { const int ti = u.pm; const int b = ti / 65, i = ti % 65; return ((long)b * SEQ + 254 * i - 2) * DM * 2; }
;     __device__ __forceinline__ long b_off(const Unit& u) const { return (long)u.pn * 256 * DM * 2; }
; template <class Epi, class Sched>
; __device__ __forceinline__ void gemm_phase(LAS unsigned char* lds, const Gemm g, const Sched& S, const Epi& E) {
;     ...
;     for (;;) {
;         const bool has_next = S.next(ui + 1, nxt);
;         const char* nA = has_next ? (const char*)g.A + S.a_off(nxt) : cA; const char* nB = has_next ? (const char*)g.Bt + S.b_off(nxt) : cB;
;         for (int t = 0; t < nt; t += 2) {
;             const bool last = (t == nt - 2);
;             const char* a1 = cA + (size_t)(t + 1) * kstep;
;             const char* a2 = last ? nA : cA + (size_t)(t + 2) * kstep; const char* b2 = last ? nB : cB + (size_t)(t + 2) * kstep;
;     ...
; #pragma unroll
;         for (int a = 0; a < 2; ++a)
; #pragma unroll
;             for (int b = 0; b < 2; ++b)
; #pragma unroll
;                 for (int m = 0; m < 4; ++m)
; #pragma unroll
;                     for (int n = 0; n < 2; ++n) acc[a][b][m][n] = (f32x4){0.f, 0.f, 0.f, 0.f};
;         }
;         cur = nxt; cA = nA; cB = nB; ++ui;
.LBB0_1274:
	s_add_u32 s49, s18, 0x100
	v_mov_b32_e32 v0, 0
	s_addc_u32 s50, s19, 0
	s_mov_b32 s51, -2
	s_waitcnt lgkmcnt(0)
	v_mov_b32_e32 v1, v0
	v_mov_b32_e32 v2, v0
	v_mov_b32_e32 v3, v0
	v_mov_b32_e32 v4, v0
	v_mov_b32_e32 v5, v0
	v_mov_b32_e32 v6, v0
	v_mov_b32_e32 v7, v0
	v_mov_b32_e32 v16, v0
	v_mov_b32_e32 v17, v0
	v_mov_b32_e32 v18, v0
	v_mov_b32_e32 v19, v0
	v_mov_b32_e32 v20, v0
	v_mov_b32_e32 v21, v0
	v_mov_b32_e32 v22, v0
	v_mov_b32_e32 v23, v0
	v_mov_b32_e32 v32, v0
	v_mov_b32_e32 v33, v0
	v_mov_b32_e32 v34, v0
	v_mov_b32_e32 v35, v0
	v_mov_b32_e32 v36, v0
	v_mov_b32_e32 v37, v0
	v_mov_b32_e32 v38, v0
	v_mov_b32_e32 v39, v0
	v_mov_b32_e32 v48, v0
	v_mov_b32_e32 v49, v0
	v_mov_b32_e32 v50, v0
	v_mov_b32_e32 v51, v0
	v_mov_b32_e32 v52, v0
	v_mov_b32_e32 v53, v0
	v_mov_b32_e32 v54, v0
	v_mov_b32_e32 v55, v0
	v_mov_b32_e32 v8, v0
	v_mov_b32_e32 v9, v0
	v_mov_b32_e32 v10, v0
	v_mov_b32_e32 v11, v0
	v_mov_b32_e32 v12, v0
	v_mov_b32_e32 v13, v0
	v_mov_b32_e32 v14, v0
	v_mov_b32_e32 v15, v0
	v_mov_b32_e32 v24, v0
	v_mov_b32_e32 v25, v0
	v_mov_b32_e32 v26, v0
	v_mov_b32_e32 v27, v0
	v_mov_b32_e32 v28, v0
	v_mov_b32_e32 v29, v0
	v_mov_b32_e32 v30, v0
	v_mov_b32_e32 v31, v0
	v_mov_b32_e32 v40, v0
	v_mov_b32_e32 v41, v0
	v_mov_b32_e32 v42, v0
	v_mov_b32_e32 v43, v0
	v_mov_b32_e32 v44, v0
	v_mov_b32_e32 v45, v0
	v_mov_b32_e32 v46, v0
	v_mov_b32_e32 v47, v0
	v_mov_b32_e32 v56, v0
	v_mov_b32_e32 v57, v0
	v_mov_b32_e32 v58, v0
	v_mov_b32_e32 v59, v0
	v_mov_b32_e32 v60, v0
	v_mov_b32_e32 v61, v0
	v_mov_b32_e32 v62, v0
	v_mov_b32_e32 v63, v0
	v_mov_b32_e32 v64, v0
	v_mov_b32_e32 v65, v0
	v_mov_b32_e32 v66, v0
	v_mov_b32_e32 v67, v0
	v_mov_b32_e32 v68, v0
	v_mov_b32_e32 v69, v0
	v_mov_b32_e32 v70, v0
	v_mov_b32_e32 v71, v0
	v_mov_b32_e32 v80, v0
	v_mov_b32_e32 v81, v0
	v_mov_b32_e32 v82, v0
	v_mov_b32_e32 v83, v0
	v_mov_b32_e32 v84, v0
	v_mov_b32_e32 v85, v0
	v_mov_b32_e32 v86, v0
	v_mov_b32_e32 v87, v0
	v_mov_b32_e32 v98, v0
	v_mov_b32_e32 v99, v0
	v_mov_b32_e32 v100, v0
	v_mov_b32_e32 v101, v0
	v_mov_b32_e32 v102, v0
	v_mov_b32_e32 v103, v0
	v_mov_b32_e32 v104, v0
	v_mov_b32_e32 v105, v0
	v_mov_b32_e32 v114, v0
	v_mov_b32_e32 v115, v0
	v_mov_b32_e32 v116, v0
	v_mov_b32_e32 v117, v0
	v_mov_b32_e32 v122, v0
	v_mov_b32_e32 v123, v0
	v_mov_b32_e32 v124, v0
	v_mov_b32_e32 v125, v0
	v_mov_b32_e32 v72, v0
	v_mov_b32_e32 v73, v0
	v_mov_b32_e32 v74, v0
	v_mov_b32_e32 v75, v0
	v_mov_b32_e32 v76, v0
	v_mov_b32_e32 v77, v0
	v_mov_b32_e32 v78, v0
	v_mov_b32_e32 v79, v0
	v_mov_b32_e32 v88, v0
	v_mov_b32_e32 v89, v0
	v_mov_b32_e32 v90, v0
	v_mov_b32_e32 v91, v0
	v_mov_b32_e32 v92, v0
	v_mov_b32_e32 v93, v0
	v_mov_b32_e32 v94, v0
	v_mov_b32_e32 v95, v0
	v_mov_b32_e32 v106, v0
	v_mov_b32_e32 v107, v0
	v_mov_b32_e32 v108, v0
	v_mov_b32_e32 v109, v0
	v_mov_b32_e32 v110, v0
	v_mov_b32_e32 v111, v0
	v_mov_b32_e32 v112, v0
	v_mov_b32_e32 v113, v0
	v_mov_b32_e32 v130, v0
	v_mov_b32_e32 v131, v0
	v_mov_b32_e32 v132, v0
	v_mov_b32_e32 v133, v0
	v_mov_b32_e32 v142, v0
	v_mov_b32_e32 v143, v0
	v_mov_b32_e32 v144, v0
	v_mov_b32_e32 v145, v0
	s_nop 0
	s_nop 0
	s_nop 0
	s_nop 0
	s_nop 0
	s_nop 0
	s_nop 0
	s_nop 0
	s_nop 0
	s_nop 0
	s_nop 0
	s_nop 0
	s_nop 0
	s_nop 0
